# stack: passC walk + passC state-update LDS batching + SB finalize/V-hoist + ss_in hoist + flat->global
# baseline (speedup 1.0000x reference)
; #define LAS __attribute__((address_space(3)))
; DI unsigned pk2(float lo, float hi) { f32x2_t f = {lo, hi}; bf16x2_t v = __builtin_convertvector(f, bf16x2_t); return __builtin_bit_cast(unsigned, v); }
; DI f32x4 mfma16(bf16x8 a, bf16x8 b, f32x4 c) { return __builtin_amdgcn_mfma_f32_16x16x32_bf16(a, b, c, 0, 0, 0); }
; DI void hgrn_passC(const Params& P, LAS unsigned char* lds, int u) {
;     ...
;         __syncthreads();
;         const bf16x8 bi = *(const LAS bf16x8*)(IT + (16 * w + r16) * 80 + g * 16);
; #pragma unroll
;         for (int ci = 0; ci < 2; ++ci) { const bf16x8 a = *(const LAS bf16x8*)(Ps + (16 * ci + r16) * 80 + g * 16);
;             ao[ci] = mfma16(a, bi, ao[ci]);
; #pragma unroll
;             for (int j = 0; j < 4; ++j) Os[(16 * ci + 4 * g + j) * 132 + 16 * w + r16] = ao[ci][j]; }
; #pragma unroll
;         for (int dt = 0; dt < 8; ++dt) {
;             const bf16x8 a = *(const LAS bf16x8*)(KT + (16 * dt + r16) * 80 + g * 16);
;             acc[dt] = mfma16(a, bi, acc[dt]);
;             const f32x4 dv = *(const LAS f32x4*)(dec + 16 * dt + 4 * g);
;             acc[dt] *= dv;
;             u32x2 pw; pw.x = pk2(acc[dt][0], acc[dt][1]); pw.y = pk2(acc[dt][2], acc[dt][3]);
;             *(LAS u32x2*)(ST + (16 * w + r16) * 272 + (16 * dt + 4 * g) * 2) = pw;
;         }
.LBB0_95:
	s_or_b64 exec, exec, s[34:35]
	s_waitcnt lgkmcnt(0)
	s_barrier
	ds_read_b128 v[96:99], v90 offset:27648
	ds_read_b128 v[100:103], v91 offset:37888
	v_ashrrev_i32_e32 v73, 31, v72
	s_waitcnt lgkmcnt(0)
	v_mfma_f32_16x16x32_bf16 v[60:63], v[100:103], v[96:99], v[60:63]
	s_mov_b32 s8, 0x9600000
	s_add_u32 s6, s6, 0x60000
	s_addc_u32 s7, s7, 0
	s_nop 4
	ds_write2_b32 v92, v60, v61 offset1:132
	v_add_u32_e32 v60, 0x400, v92
	ds_write2_b32 v60, v62, v63 offset0:8 offset1:140
	ds_read_b128 v[60:63], v93 offset:37888
	v_lshl_add_u64 v[70:71], v[70:71], 0, s[72:73]
	s_cmp_lg_u32 s6, 0x300000
	s_waitcnt lgkmcnt(0)
	v_mfma_f32_16x16x32_bf16 v[60:63], v[60:63], v[96:99], v[64:67]
	s_nop 7
	ds_write_b32 v94, v60
	v_add_u32_e32 v60, 0x2200, v92
	ds_write2_b32 v60, v61, v62 offset0:68 offset1:200
	ds_write_b32 v92, v63 offset:10032
	ds_read_b128 v[152:155], v91 offset:17408
	ds_read_b128 v[156:159], v93 offset:17408
	ds_read_b128 v[160:163], v91 offset:19968
	ds_read_b128 v[164:167], v91 offset:21248
	ds_read_b128 v[168:171], v91 offset:22528
	ds_read_b128 v[172:175], v91 offset:23808
	ds_read_b128 v[176:179], v91 offset:25088
	ds_read_b128 v[180:183], v91 offset:26368
	ds_read_b128 v[184:187], v77
	ds_read_b128 v[188:191], v77 offset:64
	ds_read_b128 v[192:195], v77 offset:128
	ds_read_b128 v[196:199], v77 offset:192
	ds_read_b128 v[200:203], v77 offset:256
	ds_read_b128 v[204:207], v77 offset:320
	ds_read_b128 v[208:211], v77 offset:384
	ds_read_b128 v[212:215], v77 offset:448
	s_waitcnt lgkmcnt(0)
	v_mfma_f32_16x16x32_bf16 v[32:35], v[152:155], v[96:99], v[32:35]
	v_mfma_f32_16x16x32_bf16 v[28:31], v[156:159], v[96:99], v[28:31]
	v_mfma_f32_16x16x32_bf16 v[24:27], v[160:163], v[96:99], v[24:27]
	v_mfma_f32_16x16x32_bf16 v[20:23], v[164:167], v[96:99], v[20:23]
	v_mfma_f32_16x16x32_bf16 v[16:19], v[168:171], v[96:99], v[16:19]
	v_mfma_f32_16x16x32_bf16 v[12:15], v[172:175], v[96:99], v[12:15]
	v_mfma_f32_16x16x32_bf16 v[8:11], v[176:179], v[96:99], v[8:11]
	v_mfma_f32_16x16x32_bf16 v[4:7], v[180:183], v[96:99], v[4:7]
	s_nop 1
	v_pk_mul_f32 v[34:35], v[34:35], v[186:187]
	v_pk_mul_f32 v[32:33], v[32:33], v[184:185]
	v_cvt_pk_bf16_f32 v61, v34, v35
	v_cvt_pk_bf16_f32 v60, v32, v33
	ds_write_b64 v75, v[60:61] offset:40448
	v_pk_mul_f32 v[30:31], v[30:31], v[190:191]
	v_pk_mul_f32 v[28:29], v[28:29], v[188:189]
	v_cvt_pk_bf16_f32 v61, v30, v31
	v_cvt_pk_bf16_f32 v60, v28, v29
	ds_write_b64 v95, v[60:61] offset:40448
	v_pk_mul_f32 v[26:27], v[26:27], v[194:195]
	v_pk_mul_f32 v[24:25], v[24:25], v[192:193]
	v_cvt_pk_bf16_f32 v61, v26, v27
	v_cvt_pk_bf16_f32 v60, v24, v25
	ds_write_b64 v75, v[60:61] offset:40512
	v_pk_mul_f32 v[22:23], v[22:23], v[198:199]
	v_pk_mul_f32 v[20:21], v[20:21], v[196:197]
	v_cvt_pk_bf16_f32 v61, v22, v23
	v_cvt_pk_bf16_f32 v60, v20, v21
	ds_write_b64 v75, v[60:61] offset:40544
	v_pk_mul_f32 v[18:19], v[18:19], v[202:203]
	v_pk_mul_f32 v[16:17], v[16:17], v[200:201]
	v_cvt_pk_bf16_f32 v61, v18, v19
	v_cvt_pk_bf16_f32 v60, v16, v17
	ds_write_b64 v75, v[60:61] offset:40576
	v_pk_mul_f32 v[14:15], v[14:15], v[206:207]
	v_pk_mul_f32 v[12:13], v[12:13], v[204:205]
	v_cvt_pk_bf16_f32 v61, v14, v15
	v_cvt_pk_bf16_f32 v60, v12, v13
	ds_write_b64 v75, v[60:61] offset:40608
	v_pk_mul_f32 v[10:11], v[10:11], v[210:211]
	v_pk_mul_f32 v[8:9], v[8:9], v[208:209]
	v_cvt_pk_bf16_f32 v61, v10, v11
	v_cvt_pk_bf16_f32 v60, v8, v9
	ds_write_b64 v75, v[60:61] offset:40640
	v_pk_mul_f32 v[6:7], v[6:7], v[214:215]
	v_pk_mul_f32 v[4:5], v[4:5], v[212:213]
	v_cvt_pk_bf16_f32 v61, v6, v7
	v_cvt_pk_bf16_f32 v60, v4, v5
	ds_write_b64 v75, v[60:61] offset:40672
	s_waitcnt lgkmcnt(0)
	s_barrier
; #define LAS __attribute__((address_space(3)))
; DI unsigned pk2(float lo, float hi) { f32x2_t f = {lo, hi}; bf16x2_t v = __builtin_convertvector(f, bf16x2_t); return __builtin_bit_cast(unsigned, v); }
; DI float silu(float v) { return v / (1.f + __expf(-v)); }
; DI void hgrn_passC(const Params& P, LAS unsigned char* lds, int u) {
;     ...
;         __syncthreads();
;         { const f32x4 o0 = *(const LAS f32x4*)(Os + nc * 132 + nv0), o1 = *(const LAS f32x4*)(Os + nc * 132 + nv0 + 4);
;           float ss = (o0.x * o0.x + o0.y * o0.y) + (o0.z * o0.z + o0.w * o0.w) + (o1.x * o1.x + o1.y * o1.y) + (o1.z * o1.z + o1.w * o1.w);
;           ss += __shfl_xor(ss, 1); ss += __shfl_xor(ss, 2); ss += __shfl_xor(ss, 4); ss += __shfl_xor(ss, 8);
;           const float r = rsqrtf(ss * (1.f / 128.f) + EPS);
;           u32x4 wv;
;           wv.x = pk2(o0.x * r * ng0.x * silu(bflo(gv.x)), o0.y * r * ng0.y * silu(bfhi(gv.x)));
;           wv.y = pk2(o0.z * r * ng0.z * silu(bflo(gv.y)), o0.w * r * ng0.w * silu(bfhi(gv.y)));
;           wv.z = pk2(o1.x * r * ng1.x * silu(bflo(gv.z)), o1.y * r * ng1.y * silu(bfhi(gv.z)));
;           wv.w = pk2(o1.z * r * ng1.z * silu(bflo(gv.w)), o1.w * r * ng1.w * silu(bfhi(gv.w)));
;           *(u32x4*)(Y + (size_t)(tok0 + ch * 32 + nc) * DM + 1024 + h * 128 + nv0) = wv; }
;     }
	ds_read_b128 v[64:67], v78
	ds_read_b128 v[60:63], v78 offset:16
	s_waitcnt lgkmcnt(0)
	v_pk_mul_f32 v[96:97], v[66:67], v[66:67]
	v_pk_mul_f32 v[98:99], v[64:65], v[64:65]
	s_nop 0
	v_pk_mov_b32 v[100:101], v[98:99], v[96:97] op_sel:[1,0]
	v_mov_b32_e32 v99, v97
	v_pk_add_f32 v[96:97], v[100:101], v[98:99]
	v_pk_mul_f32 v[98:99], v[62:63], v[62:63]
	v_pk_mul_f32 v[100:101], v[60:61], v[60:61]
	v_mov_b32_e32 v102, v98
	v_mov_b32_e32 v103, v100
	v_mov_b32_e32 v100, v99
	v_pk_add_f32 v[98:99], v[102:103], v[100:101]
	v_add_f32_e32 v74, v96, v97
	v_add_f32_e32 v74, v74, v99
	v_add_f32_e32 v74, v98, v74
	ds_bpermute_b32 v96, v79, v74
	s_waitcnt vmcnt(0)
	v_lshlrev_b32_e32 v98, 16, v56
	v_and_b32_e32 v56, 0xffff0000, v56
	v_mul_f32_e32 v97, 0xbfb8aa3b, v56
	v_exp_f32_e32 v97, v97
	s_waitcnt lgkmcnt(0)
	v_add_f32_e32 v74, v74, v96
	ds_bpermute_b32 v96, v80, v74
	s_waitcnt lgkmcnt(0)
	v_add_f32_e32 v74, v74, v96
	ds_bpermute_b32 v96, v81, v74
	s_waitcnt lgkmcnt(0)
	v_add_f32_e32 v74, v74, v96
	ds_bpermute_b32 v96, v82, v74
	s_waitcnt lgkmcnt(0)
	v_add_f32_e32 v74, v74, v96
	v_fmamk_f32 v74, v74, 0x3c000000, v229
	v_cmp_gt_f32_e32 vcc, s33, v74
	v_mul_f32_e32 v96, 0x4b800000, v74
	s_nop 0
	v_cndmask_b32_e32 v74, v74, v96, vcc
	v_rsq_f32_e32 v74, v74
	s_nop 0
	v_mul_f32_e32 v96, 0x45800000, v74
	v_cndmask_b32_e32 v74, v74, v96, vcc
	v_mul_f32_e32 v96, 0xbfb8aa3b, v98
	v_exp_f32_e32 v96, v96
	v_pk_mul_f32 v[64:65], v[64:65], v[74:75] op_sel_hi:[1,0]
	v_pk_mul_f32 v[66:67], v[66:67], v[74:75] op_sel_hi:[1,0]
	v_pk_mul_f32 v[64:65], v[48:49], v[64:65]
	v_pk_add_f32 v[96:97], v[96:97], 1.0 op_sel_hi:[1,0]
	v_pk_mul_f32 v[66:67], v[50:51], v[66:67]
	v_div_scale_f32 v99, s[12:13], v97, v97, v56
	v_rcp_f32_e32 v100, v99
	v_pk_mul_f32 v[60:61], v[60:61], v[74:75] op_sel_hi:[1,0]
	v_pk_mul_f32 v[62:63], v[62:63], v[74:75] op_sel_hi:[1,0]
	v_pk_mul_f32 v[60:61], v[52:53], v[60:61]
	v_fma_f32 v101, -v99, v100, 1.0
	v_fmac_f32_e32 v100, v101, v100
	v_div_scale_f32 v101, vcc, v56, v97, v56
	v_mul_f32_e32 v102, v101, v100
	v_fma_f32 v103, -v99, v102, v101
	v_fmac_f32_e32 v102, v103, v100
	v_fma_f32 v99, -v99, v102, v101
	v_div_fmas_f32 v99, v99, v100, v102
	v_div_fixup_f32 v97, v99, v97, v56
	v_div_scale_f32 v56, s[12:13], v96, v96, v98
	v_rcp_f32_e32 v99, v56
	v_pk_mul_f32 v[62:63], v[54:55], v[62:63]
	v_fma_f32 v100, -v56, v99, 1.0
	v_fmac_f32_e32 v99, v100, v99
	v_div_scale_f32 v100, vcc, v98, v96, v98
	v_mul_f32_e32 v101, v100, v99
	v_fma_f32 v102, -v56, v101, v100
	v_fmac_f32_e32 v101, v102, v99
	v_fma_f32 v56, -v56, v101, v100
	v_div_fmas_f32 v56, v56, v99, v101
	v_div_fixup_f32 v96, v56, v96, v98
	v_pk_mul_f32 v[64:65], v[96:97], v[64:65]
	v_lshlrev_b32_e32 v96, 16, v57
	v_and_b32_e32 v57, 0xffff0000, v57
	v_cvt_pk_bf16_f32 v56, v64, v65
	v_mul_f32_e32 v64, 0xbfb8aa3b, v96
	v_mul_f32_e32 v65, 0xbfb8aa3b, v57
	v_exp_f32_e32 v64, v64
	v_exp_f32_e32 v65, v65
	s_nop 0
	v_pk_add_f32 v[64:65], v[64:65], 1.0 op_sel_hi:[1,0]
	s_nop 0
	v_div_scale_f32 v97, s[12:13], v65, v65, v57
	v_rcp_f32_e32 v98, v97
	s_nop 0
	v_fma_f32 v99, -v97, v98, 1.0
	v_fmac_f32_e32 v98, v99, v98
	v_div_scale_f32 v99, vcc, v57, v65, v57
	v_mul_f32_e32 v100, v99, v98
	v_fma_f32 v101, -v97, v100, v99
	v_fmac_f32_e32 v100, v101, v98
	v_fma_f32 v97, -v97, v100, v99
	v_div_fmas_f32 v97, v97, v98, v100
	v_div_fixup_f32 v65, v97, v65, v57
	v_div_scale_f32 v57, s[12:13], v64, v64, v96
	v_rcp_f32_e32 v97, v57
	s_nop 0
	v_fma_f32 v98, -v57, v97, 1.0
	v_fmac_f32_e32 v97, v98, v97
	v_div_scale_f32 v98, vcc, v96, v64, v96
	v_mul_f32_e32 v99, v98, v97
	v_fma_f32 v100, -v57, v99, v98
	v_fmac_f32_e32 v99, v100, v97
	v_fma_f32 v57, -v57, v99, v98
	v_div_fmas_f32 v57, v57, v97, v99
	v_div_fixup_f32 v64, v57, v64, v96
	v_pk_mul_f32 v[64:65], v[64:65], v[66:67]
	v_lshlrev_b32_e32 v66, 16, v58
	v_and_b32_e32 v58, 0xffff0000, v58
	v_cvt_pk_bf16_f32 v57, v64, v65
	v_mul_f32_e32 v64, 0xbfb8aa3b, v66
	v_mul_f32_e32 v65, 0xbfb8aa3b, v58
	v_exp_f32_e32 v64, v64
	v_exp_f32_e32 v65, v65
	s_nop 0
	v_pk_add_f32 v[64:65], v[64:65], 1.0 op_sel_hi:[1,0]
	s_nop 0
	v_div_scale_f32 v67, s[12:13], v65, v65, v58
	v_rcp_f32_e32 v96, v67
	s_nop 0
	v_fma_f32 v97, -v67, v96, 1.0
	v_fmac_f32_e32 v96, v97, v96
	v_div_scale_f32 v97, vcc, v58, v65, v58
	v_mul_f32_e32 v98, v97, v96
	v_fma_f32 v99, -v67, v98, v97
	v_fmac_f32_e32 v98, v99, v96
	v_fma_f32 v67, -v67, v98, v97
	v_div_fmas_f32 v67, v67, v96, v98
	v_div_fixup_f32 v65, v67, v65, v58
	v_div_scale_f32 v58, s[12:13], v64, v64, v66
	v_rcp_f32_e32 v67, v58
	s_nop 0
	v_fma_f32 v96, -v58, v67, 1.0
	v_fmac_f32_e32 v67, v96, v67
	v_div_scale_f32 v96, vcc, v66, v64, v66
	v_mul_f32_e32 v97, v96, v67
	v_fma_f32 v98, -v58, v97, v96
	v_fmac_f32_e32 v97, v98, v67
	v_fma_f32 v58, -v58, v97, v96
	v_div_fmas_f32 v58, v58, v67, v97
	v_div_fixup_f32 v64, v58, v64, v66
	v_pk_mul_f32 v[60:61], v[64:65], v[60:61]
	v_lshlrev_b32_e32 v64, 16, v59
	v_and_b32_e32 v59, 0xffff0000, v59
	v_cvt_pk_bf16_f32 v58, v60, v61
	v_mul_f32_e32 v60, 0xbfb8aa3b, v64
	v_mul_f32_e32 v61, 0xbfb8aa3b, v59
	v_exp_f32_e32 v60, v60
	v_exp_f32_e32 v61, v61
	s_nop 0
	v_pk_add_f32 v[60:61], v[60:61], 1.0 op_sel_hi:[1,0]
	s_nop 0
	v_div_scale_f32 v65, s[12:13], v61, v61, v59
	v_rcp_f32_e32 v66, v65
	s_nop 0
	v_fma_f32 v67, -v65, v66, 1.0
	v_fmac_f32_e32 v66, v67, v66
	v_div_scale_f32 v67, vcc, v59, v61, v59
	v_mul_f32_e32 v74, v67, v66
	v_fma_f32 v96, -v65, v74, v67
	v_fmac_f32_e32 v74, v96, v66
	v_fma_f32 v65, -v65, v74, v67
	v_div_fmas_f32 v65, v65, v66, v74
	v_div_fixup_f32 v61, v65, v61, v59
	v_div_scale_f32 v59, s[12:13], v60, v60, v64
	v_rcp_f32_e32 v65, v59
	s_nop 0
	v_fma_f32 v66, -v59, v65, 1.0
	v_fmac_f32_e32 v65, v66, v65
	v_div_scale_f32 v66, vcc, v64, v60, v64
	v_mul_f32_e32 v67, v66, v65
	v_fma_f32 v74, -v59, v67, v66
	v_fmac_f32_e32 v67, v74, v65
	v_fma_f32 v59, -v59, v67, v66
	v_div_fmas_f32 v59, v59, v65, v67
	v_div_fixup_f32 v60, v59, v60, v64
	v_pk_mul_f32 v[60:61], v[60:61], v[62:63]
	s_nop 0
	v_cvt_pk_bf16_f32 v59, v60, v61
	v_lshlrev_b64 v[60:61], 12, v[72:73]
	v_lshl_add_u64 v[60:61], s[4:5], 0, v[60:61]
	v_lshl_add_u64 v[60:61], v[60:61], 0, s[10:11]
	v_lshl_add_u64 v[60:61], v[60:61], 0, v[0:1]
	v_add_co_u32_e32 v60, vcc, s8, v60
	v_add_u32_e32 v72, 32, v72
	s_nop 0
	v_addc_co_u32_e32 v61, vcc, 0, v61, vcc
	global_store_dwordx4 v[60:61], v[56:59], off offset:2048
	s_cbranch_scc0 .LBB0_85

; DI unsigned f2bf(float f) { unsigned u = __builtin_bit_cast(unsigned, f); return (u + 0x7fffu + ((u >> 16) & 1u)) >> 16; }
;     DI void operator()(const f32x4 (&acc)[2][2][4][2], const Unit& u, int wr, int wc, int fr, int fq) const {
;     ...
;                     for (int m = 0; m < 4; ++m) { const int row = rowi + ai * HALF + m * 16;
;                         const float rs_ = ss_in ? rsqrtf(ss_in[row0 + ai * HALF + m * 16] * (1.f / DM) + EPS) : 1.f;
; #pragma unroll
;                         for (int bj = 0; bj < 2; ++bj)
; #pragma unroll
;                             for (int n = 0; n < 2; ++n)
; #pragma unroll
;                                 for (int j = 0; j < 4; ++j) base[(size_t)(col0 + bj * HALF + 4 * n + j) * ldt + row] = (bf16_t)f2bf(acc[ai][bj][m][n][j] * rs_); }
.LBB0_452:
	s_and_b64 vcc, exec, s[24:25]
	s_cbranch_vccz .LBB0_470
	v_readlane_b32 s16, v255, 4
	v_readlane_b32 s17, v255, 5
	v_mov_b32_e32 v164, 1.0
	s_andn2_b64 vcc, exec, s[16:17]
	v_cndmask_b32_e64 v0, 0, 1, s[16:17]
	v_cmp_ne_u32_e64 s[44:45], 1, v0
	v_ashrrev_i32_e32 v131, 31, v130
	v_mov_b32_e32 v162, 1.0
	s_cbranch_vccnz .LBB0_455
	v_ashrrev_i32_e32 v131, 31, v130
	v_lshl_add_u64 v[132:133], v[130:131], 2, s[74:75]
	global_load_dword v232, v[132:133], off
	global_load_dword v233, v[132:133], off offset:64
	global_load_dword v234, v[132:133], off offset:128
	global_load_dword v235, v[132:133], off offset:192
	global_load_dword v236, v[132:133], off offset:512
	global_load_dword v237, v[132:133], off offset:576
	global_load_dword v238, v[132:133], off offset:640
	global_load_dword v239, v[132:133], off offset:704
	s_waitcnt vmcnt(0) lgkmcnt(0)
	v_fmamk_f32 v232, v232, 0x3a000000, v229
	v_mul_f32_e32 v246, 0x4b800000, v232
	v_cmp_gt_f32_e32 vcc, s33, v232
	s_nop 1
	v_cndmask_b32_e32 v232, v232, v246, vcc
	v_rsq_f32_e32 v232, v232
	s_nop 0
	v_mul_f32_e32 v246, 0x45800000, v232
	v_cndmask_b32_e32 v232, v232, v246, vcc
	v_fmamk_f32 v233, v233, 0x3a000000, v229
	v_mul_f32_e32 v246, 0x4b800000, v233
	v_cmp_gt_f32_e32 vcc, s33, v233
	s_nop 1
	v_cndmask_b32_e32 v233, v233, v246, vcc
	v_rsq_f32_e32 v233, v233
	s_nop 0
	v_mul_f32_e32 v246, 0x45800000, v233
	v_cndmask_b32_e32 v233, v233, v246, vcc
	v_fmamk_f32 v234, v234, 0x3a000000, v229
	v_mul_f32_e32 v246, 0x4b800000, v234
	v_cmp_gt_f32_e32 vcc, s33, v234
	s_nop 1
	v_cndmask_b32_e32 v234, v234, v246, vcc
	v_rsq_f32_e32 v234, v234
	s_nop 0
	v_mul_f32_e32 v246, 0x45800000, v234
	v_cndmask_b32_e32 v234, v234, v246, vcc
	v_fmamk_f32 v235, v235, 0x3a000000, v229
	v_mul_f32_e32 v246, 0x4b800000, v235
	v_cmp_gt_f32_e32 vcc, s33, v235
	s_nop 1
	v_cndmask_b32_e32 v235, v235, v246, vcc
	v_rsq_f32_e32 v235, v235
	s_nop 0
	v_mul_f32_e32 v246, 0x45800000, v235
	v_cndmask_b32_e32 v235, v235, v246, vcc
	v_fmamk_f32 v236, v236, 0x3a000000, v229
	v_mul_f32_e32 v246, 0x4b800000, v236
	v_cmp_gt_f32_e32 vcc, s33, v236
	s_nop 1
	v_cndmask_b32_e32 v236, v236, v246, vcc
	v_rsq_f32_e32 v236, v236
	s_nop 0
	v_mul_f32_e32 v246, 0x45800000, v236
	v_cndmask_b32_e32 v236, v236, v246, vcc
	v_fmamk_f32 v237, v237, 0x3a000000, v229
	v_mul_f32_e32 v246, 0x4b800000, v237
	v_cmp_gt_f32_e32 vcc, s33, v237
	s_nop 1
	v_cndmask_b32_e32 v237, v237, v246, vcc
	v_rsq_f32_e32 v237, v237
	s_nop 0
	v_mul_f32_e32 v246, 0x45800000, v237
	v_cndmask_b32_e32 v237, v237, v246, vcc
	v_fmamk_f32 v238, v238, 0x3a000000, v229
	v_mul_f32_e32 v246, 0x4b800000, v238
	v_cmp_gt_f32_e32 vcc, s33, v238
	s_nop 1
	v_cndmask_b32_e32 v238, v238, v246, vcc
	v_rsq_f32_e32 v238, v238
	s_nop 0
	v_mul_f32_e32 v246, 0x45800000, v238
	v_cndmask_b32_e32 v238, v238, v246, vcc
	v_fmamk_f32 v239, v239, 0x3a000000, v229
	v_mul_f32_e32 v246, 0x4b800000, v239
	v_cmp_gt_f32_e32 vcc, s33, v239
	s_nop 1
	v_cndmask_b32_e32 v239, v239, v246, vcc
	v_rsq_f32_e32 v239, v239
	s_nop 0
	v_mul_f32_e32 v246, 0x45800000, v239
	v_cndmask_b32_e32 v239, v239, v246, vcc
	v_mov_b32_e32 v162, v232
.LBB0_455:
	v_readlane_b32 s16, v255, 2
	s_cmp_lt_u32 s76, 32
	v_readlane_b32 s17, v255, 3
	s_cselect_b32 s3, s17, s99
	s_cselect_b32 s13, s16, s98
	v_mov_b32_e32 v133, s3
	s_and_b32 s3, s12, 0x1f00
	v_add_u32_e32 v134, s3, v251
	v_mov_b32_e32 v132, s13
	v_ashrrev_i32_e32 v135, 31, v134
	v_mul_f32_e32 v0, v126, v162
	v_lshl_add_u64 v[132:133], v[134:135], 1, v[132:133]
	v_bfe_u32 v134, v0, 16, 1
	v_add3_u32 v0, v0, v134, s92
	v_lshlrev_b32_e32 v134, 14, v248
	v_lshl_or_b32 v166, s8, 22, v134
	v_mov_b32_e32 v167, v1
	v_lshl_add_u64 v[134:135], v[132:133], 0, v[166:167]
	global_store_short_d16_hi v[134:135], v0, off
	v_mul_f32_e32 v0, v127, v162
	v_bfe_u32 v136, v0, 16, 1
	v_add3_u32 v138, v0, v136, s92
	v_or_b32_e32 v0, 0x4000, v166
	v_lshl_add_u64 v[136:137], v[132:133], 0, v[0:1]
	global_store_short_d16_hi v[136:137], v138, off
	v_mul_f32_e32 v136, v128, v162
	v_bfe_u32 v137, v136, 16, 1
	v_add3_u32 v140, v136, v137, s92
	v_or_b32_e32 v136, 0x8000, v166
	v_mov_b32_e32 v137, v1
	v_lshl_add_u64 v[138:139], v[132:133], 0, v[136:137]
	global_store_short_d16_hi v[138:139], v140, off
	v_mul_f32_e32 v138, v129, v162
	v_bfe_u32 v139, v138, 16, 1
	v_add3_u32 v142, v138, v139, s92
	v_or_b32_e32 v138, 0xc000, v166
	v_mov_b32_e32 v139, v1
	v_lshl_add_u64 v[140:141], v[132:133], 0, v[138:139]
	global_store_short_d16_hi v[140:141], v142, off
	v_mul_f32_e32 v140, v122, v162
	v_bfe_u32 v141, v140, 16, 1
	v_add3_u32 v144, v140, v141, s92
	v_or_b32_e32 v140, 0x10000, v166
	v_mov_b32_e32 v141, v1
	v_lshl_add_u64 v[142:143], v[132:133], 0, v[140:141]
	global_store_short_d16_hi v[142:143], v144, off
	v_mul_f32_e32 v142, v123, v162
	v_bfe_u32 v143, v142, 16, 1
	v_add3_u32 v146, v142, v143, s92
	v_or_b32_e32 v142, 0x14000, v166
	v_mov_b32_e32 v143, v1
	v_lshl_add_u64 v[144:145], v[132:133], 0, v[142:143]
	global_store_short_d16_hi v[144:145], v146, off
	v_mul_f32_e32 v144, v124, v162
	v_bfe_u32 v145, v144, 16, 1
	v_add3_u32 v148, v144, v145, s92
	v_or_b32_e32 v144, 0x18000, v166
	v_mov_b32_e32 v145, v1
	v_lshl_add_u64 v[146:147], v[132:133], 0, v[144:145]
	global_store_short_d16_hi v[146:147], v148, off
	v_mul_f32_e32 v146, v125, v162
	v_bfe_u32 v147, v146, 16, 1
	v_add3_u32 v150, v146, v147, s92
	v_or_b32_e32 v146, 0x1c000, v166
	v_mov_b32_e32 v147, v1
	v_lshl_add_u64 v[148:149], v[132:133], 0, v[146:147]
	global_store_short_d16_hi v[148:149], v150, off
	v_mul_f32_e32 v148, v118, v162
	v_bfe_u32 v149, v148, 16, 1
	v_add3_u32 v152, v148, v149, s92
	v_or_b32_e32 v148, 0x200000, v166
	v_mov_b32_e32 v149, v1
; DI unsigned f2bf(float f) { unsigned u = __builtin_bit_cast(unsigned, f); return (u + 0x7fffu + ((u >> 16) & 1u)) >> 16; }
;     DI void operator()(const f32x4 (&acc)[2][2][4][2], const Unit& u, int wr, int wc, int fr, int fq) const {
;     ...
;                     for (int m = 0; m < 4; ++m) { const int row = rowi + ai * HALF + m * 16;
;                         const float rs_ = ss_in ? rsqrtf(ss_in[row0 + ai * HALF + m * 16] * (1.f / DM) + EPS) : 1.f;
; #pragma unroll
;                         for (int bj = 0; bj < 2; ++bj)
; #pragma unroll
;                             for (int n = 0; n < 2; ++n)
; #pragma unroll
;                                 for (int j = 0; j < 4; ++j) base[(size_t)(col0 + bj * HALF + 4 * n + j) * ldt + row] = (bf16_t)f2bf(acc[ai][bj][m][n][j] * rs_); }
	v_lshl_add_u64 v[150:151], v[132:133], 0, v[148:149]
	global_store_short_d16_hi v[150:151], v152, off
	v_mul_f32_e32 v150, v119, v162
	v_bfe_u32 v151, v150, 16, 1
	v_add3_u32 v154, v150, v151, s92
	v_or_b32_e32 v150, 0x204000, v166
	v_mov_b32_e32 v151, v1
	v_lshl_add_u64 v[152:153], v[132:133], 0, v[150:151]
	global_store_short_d16_hi v[152:153], v154, off
	v_mul_f32_e32 v152, v120, v162
	v_bfe_u32 v153, v152, 16, 1
	v_add3_u32 v156, v152, v153, s92
	v_or_b32_e32 v152, 0x208000, v166
	v_mov_b32_e32 v153, v1
	v_lshl_add_u64 v[154:155], v[132:133], 0, v[152:153]
	global_store_short_d16_hi v[154:155], v156, off
	v_mul_f32_e32 v154, v121, v162
	v_bfe_u32 v155, v154, 16, 1
	v_add3_u32 v158, v154, v155, s92
	v_or_b32_e32 v154, 0x20c000, v166
	v_mov_b32_e32 v155, v1
	v_lshl_add_u64 v[156:157], v[132:133], 0, v[154:155]
	global_store_short_d16_hi v[156:157], v158, off
	v_mul_f32_e32 v156, v114, v162
	v_bfe_u32 v157, v156, 16, 1
	v_add3_u32 v160, v156, v157, s92
	v_or_b32_e32 v156, 0x210000, v166
	v_mov_b32_e32 v157, v1
	v_lshl_add_u64 v[158:159], v[132:133], 0, v[156:157]
	global_store_short_d16_hi v[158:159], v160, off
	v_mul_f32_e32 v158, v115, v162
	v_bfe_u32 v159, v158, 16, 1
	v_add3_u32 v163, v158, v159, s92
	v_or_b32_e32 v158, 0x214000, v166
	v_mov_b32_e32 v159, v1
	v_lshl_add_u64 v[160:161], v[132:133], 0, v[158:159]
	global_store_short_d16_hi v[160:161], v163, off
	v_mul_f32_e32 v160, v116, v162
	v_bfe_u32 v161, v160, 16, 1
	v_add3_u32 v163, v160, v161, s92
	v_or_b32_e32 v160, 0x218000, v166
	v_mov_b32_e32 v161, v1
	v_lshl_add_u64 v[168:169], v[132:133], 0, v[160:161]
	v_mul_f32_e32 v162, v117, v162
	global_store_short_d16_hi v[168:169], v163, off
	v_bfe_u32 v163, v162, 16, 1
	v_add3_u32 v165, v162, v163, s92
	v_or_b32_e32 v162, 0x21c000, v166
	v_mov_b32_e32 v163, v1
	v_lshl_add_u64 v[166:167], v[132:133], 0, v[162:163]
	s_and_b64 vcc, exec, s[44:45]
	global_store_short_d16_hi v[166:167], v165, off
	s_cbranch_vccnz .LBB0_457
	v_mov_b32_e32 v164, v233
.LBB0_457:
	v_mul_f32_e32 v165, v110, v164
	v_bfe_u32 v168, v165, 16, 1
	v_add3_u32 v165, v165, v168, s92
	global_store_short_d16_hi v[134:135], v165, off offset:32
	v_mul_f32_e32 v165, v111, v164
	v_lshl_add_u64 v[166:167], v[132:133], 0, 32
	v_bfe_u32 v168, v165, 16, 1
	v_add3_u32 v165, v165, v168, s92
	v_lshl_add_u64 v[168:169], v[166:167], 0, v[0:1]
	global_store_short_d16_hi v[168:169], v165, off
	v_mul_f32_e32 v165, v112, v164
	v_bfe_u32 v168, v165, 16, 1
	v_add3_u32 v165, v165, v168, s92
	v_lshl_add_u64 v[168:169], v[166:167], 0, v[136:137]
	global_store_short_d16_hi v[168:169], v165, off
	v_mul_f32_e32 v165, v113, v164
	v_bfe_u32 v168, v165, 16, 1
	v_add3_u32 v165, v165, v168, s92
	v_lshl_add_u64 v[168:169], v[166:167], 0, v[138:139]
	global_store_short_d16_hi v[168:169], v165, off
	v_mul_f32_e32 v165, v106, v164
	v_bfe_u32 v168, v165, 16, 1
	v_add3_u32 v165, v165, v168, s92
	v_lshl_add_u64 v[168:169], v[166:167], 0, v[140:141]
	global_store_short_d16_hi v[168:169], v165, off
	v_mul_f32_e32 v165, v107, v164
	v_bfe_u32 v168, v165, 16, 1
	v_add3_u32 v165, v165, v168, s92
	v_lshl_add_u64 v[168:169], v[166:167], 0, v[142:143]
	global_store_short_d16_hi v[168:169], v165, off
	v_mul_f32_e32 v165, v108, v164
	v_bfe_u32 v168, v165, 16, 1
	v_add3_u32 v165, v165, v168, s92
	v_lshl_add_u64 v[168:169], v[166:167], 0, v[144:145]
	global_store_short_d16_hi v[168:169], v165, off
	v_mul_f32_e32 v165, v109, v164
	v_bfe_u32 v168, v165, 16, 1
	v_add3_u32 v165, v165, v168, s92
	v_lshl_add_u64 v[168:169], v[166:167], 0, v[146:147]
	global_store_short_d16_hi v[168:169], v165, off
	v_mul_f32_e32 v165, v102, v164
	v_bfe_u32 v168, v165, 16, 1
	v_add3_u32 v165, v165, v168, s92
	v_lshl_add_u64 v[168:169], v[166:167], 0, v[148:149]
	global_store_short_d16_hi v[168:169], v165, off
	v_mul_f32_e32 v165, v103, v164
	v_bfe_u32 v168, v165, 16, 1
	v_add3_u32 v165, v165, v168, s92
	v_lshl_add_u64 v[168:169], v[166:167], 0, v[150:151]
	global_store_short_d16_hi v[168:169], v165, off
	v_mul_f32_e32 v165, v104, v164
	v_bfe_u32 v168, v165, 16, 1
	v_add3_u32 v165, v165, v168, s92
	v_lshl_add_u64 v[168:169], v[166:167], 0, v[152:153]
	global_store_short_d16_hi v[168:169], v165, off
	v_mul_f32_e32 v165, v105, v164
	v_bfe_u32 v168, v165, 16, 1
	v_add3_u32 v165, v165, v168, s92
	v_lshl_add_u64 v[168:169], v[166:167], 0, v[154:155]
	global_store_short_d16_hi v[168:169], v165, off
	v_mul_f32_e32 v165, v98, v164
	v_bfe_u32 v168, v165, 16, 1
	v_add3_u32 v165, v165, v168, s92
	v_lshl_add_u64 v[168:169], v[166:167], 0, v[156:157]
	global_store_short_d16_hi v[168:169], v165, off
	v_mul_f32_e32 v165, v99, v164
	v_bfe_u32 v168, v165, 16, 1
	v_add3_u32 v165, v165, v168, s92
	v_lshl_add_u64 v[168:169], v[166:167], 0, v[158:159]
	global_store_short_d16_hi v[168:169], v165, off
	v_mul_f32_e32 v165, v100, v164
	v_bfe_u32 v168, v165, 16, 1
	v_add3_u32 v165, v165, v168, s92
	v_lshl_add_u64 v[168:169], v[166:167], 0, v[160:161]
	v_mul_f32_e32 v164, v101, v164
	global_store_short_d16_hi v[168:169], v165, off
	v_bfe_u32 v165, v164, 16, 1
	v_add3_u32 v168, v164, v165, s92
	v_lshl_add_u64 v[164:165], v[166:167], 0, v[162:163]
	global_store_short_d16_hi v[164:165], v168, off
	v_mov_b32_e32 v164, 1.0
	s_and_b64 vcc, exec, s[44:45]
	v_mov_b32_e32 v165, 1.0
	s_cbranch_vccnz .LBB0_459
	v_mov_b32_e32 v165, v234
; DI unsigned f2bf(float f) { unsigned u = __builtin_bit_cast(unsigned, f); return (u + 0x7fffu + ((u >> 16) & 1u)) >> 16; }
;     DI void operator()(const f32x4 (&acc)[2][2][4][2], const Unit& u, int wr, int wc, int fr, int fq) const {
;     ...
;                     for (int m = 0; m < 4; ++m) { const int row = rowi + ai * HALF + m * 16;
;                         const float rs_ = ss_in ? rsqrtf(ss_in[row0 + ai * HALF + m * 16] * (1.f / DM) + EPS) : 1.f;
; #pragma unroll
;                         for (int bj = 0; bj < 2; ++bj)
; #pragma unroll
;                             for (int n = 0; n < 2; ++n)
; #pragma unroll
;                                 for (int j = 0; j < 4; ++j) base[(size_t)(col0 + bj * HALF + 4 * n + j) * ldt + row] = (bf16_t)f2bf(acc[ai][bj][m][n][j] * rs_); }
.LBB0_459:
	v_mul_f32_e32 v168, v94, v165
	v_bfe_u32 v169, v168, 16, 1
	v_add3_u32 v168, v168, v169, s92
	global_store_short_d16_hi v[134:135], v168, off offset:64
	v_mul_f32_e32 v168, v95, v165
	v_lshl_add_u64 v[166:167], v[132:133], 0, 64
	v_bfe_u32 v169, v168, 16, 1
	v_add3_u32 v170, v168, v169, s92
	v_lshl_add_u64 v[168:169], v[166:167], 0, v[0:1]
	global_store_short_d16_hi v[168:169], v170, off
	v_mul_f32_e32 v168, v96, v165
	v_bfe_u32 v169, v168, 16, 1
	v_add3_u32 v170, v168, v169, s92
	v_lshl_add_u64 v[168:169], v[166:167], 0, v[136:137]
	global_store_short_d16_hi v[168:169], v170, off
	v_mul_f32_e32 v168, v97, v165
	v_bfe_u32 v169, v168, 16, 1
	v_add3_u32 v170, v168, v169, s92
	v_lshl_add_u64 v[168:169], v[166:167], 0, v[138:139]
	global_store_short_d16_hi v[168:169], v170, off
	v_mul_f32_e32 v168, v90, v165
	v_bfe_u32 v169, v168, 16, 1
	v_add3_u32 v170, v168, v169, s92
	v_lshl_add_u64 v[168:169], v[166:167], 0, v[140:141]
	global_store_short_d16_hi v[168:169], v170, off
	v_mul_f32_e32 v168, v91, v165
	v_bfe_u32 v169, v168, 16, 1
	v_add3_u32 v170, v168, v169, s92
	v_lshl_add_u64 v[168:169], v[166:167], 0, v[142:143]
	global_store_short_d16_hi v[168:169], v170, off
	v_mul_f32_e32 v168, v92, v165
	v_bfe_u32 v169, v168, 16, 1
	v_add3_u32 v170, v168, v169, s92
	v_lshl_add_u64 v[168:169], v[166:167], 0, v[144:145]
	global_store_short_d16_hi v[168:169], v170, off
	v_mul_f32_e32 v168, v93, v165
	v_bfe_u32 v169, v168, 16, 1
	v_add3_u32 v170, v168, v169, s92
	v_lshl_add_u64 v[168:169], v[166:167], 0, v[146:147]
	global_store_short_d16_hi v[168:169], v170, off
	v_mul_f32_e32 v168, v86, v165
	v_bfe_u32 v169, v168, 16, 1
	v_add3_u32 v170, v168, v169, s92
	v_lshl_add_u64 v[168:169], v[166:167], 0, v[148:149]
	global_store_short_d16_hi v[168:169], v170, off
	v_mul_f32_e32 v168, v87, v165
	v_bfe_u32 v169, v168, 16, 1
	v_add3_u32 v170, v168, v169, s92
	v_lshl_add_u64 v[168:169], v[166:167], 0, v[150:151]
	global_store_short_d16_hi v[168:169], v170, off
	v_mul_f32_e32 v168, v88, v165
	v_bfe_u32 v169, v168, 16, 1
	v_add3_u32 v170, v168, v169, s92
	v_lshl_add_u64 v[168:169], v[166:167], 0, v[152:153]
	global_store_short_d16_hi v[168:169], v170, off
	v_mul_f32_e32 v168, v89, v165
	v_bfe_u32 v169, v168, 16, 1
	v_add3_u32 v170, v168, v169, s92
	v_lshl_add_u64 v[168:169], v[166:167], 0, v[154:155]
	global_store_short_d16_hi v[168:169], v170, off
	v_mul_f32_e32 v168, v82, v165
	v_bfe_u32 v169, v168, 16, 1
	v_add3_u32 v170, v168, v169, s92
	v_lshl_add_u64 v[168:169], v[166:167], 0, v[156:157]
	global_store_short_d16_hi v[168:169], v170, off
	v_mul_f32_e32 v168, v83, v165
	v_bfe_u32 v169, v168, 16, 1
	v_add3_u32 v170, v168, v169, s92
	v_lshl_add_u64 v[168:169], v[166:167], 0, v[158:159]
	global_store_short_d16_hi v[168:169], v170, off
	v_mul_f32_e32 v168, v84, v165
	v_bfe_u32 v169, v168, 16, 1
	v_add3_u32 v170, v168, v169, s92
	v_lshl_add_u64 v[168:169], v[166:167], 0, v[160:161]
	v_mul_f32_e32 v165, v85, v165
	global_store_short_d16_hi v[168:169], v170, off
	v_bfe_u32 v168, v165, 16, 1
	v_add3_u32 v165, v165, v168, s92
	v_lshl_add_u64 v[166:167], v[166:167], 0, v[162:163]
	s_and_b64 vcc, exec, s[44:45]
	global_store_short_d16_hi v[166:167], v165, off
	s_cbranch_vccnz .LBB0_461
	v_mov_b32_e32 v164, v235
.LBB0_461:
	v_mul_f32_e32 v165, v78, v164
	v_bfe_u32 v168, v165, 16, 1
	v_add3_u32 v165, v165, v168, s92
	s_mov_b64 s[12:13], 0x60
	global_store_short_d16_hi v[134:135], v165, off offset:96
	v_mul_f32_e32 v165, v79, v164
	v_lshl_add_u64 v[166:167], v[132:133], 0, s[12:13]
	v_bfe_u32 v168, v165, 16, 1
	v_add3_u32 v165, v165, v168, s92
	v_lshl_add_u64 v[168:169], v[166:167], 0, v[0:1]
	global_store_short_d16_hi v[168:169], v165, off
	v_mul_f32_e32 v165, v80, v164
	v_bfe_u32 v168, v165, 16, 1
	v_add3_u32 v165, v165, v168, s92
	v_lshl_add_u64 v[168:169], v[166:167], 0, v[136:137]
	global_store_short_d16_hi v[168:169], v165, off
	v_mul_f32_e32 v165, v81, v164
	v_bfe_u32 v168, v165, 16, 1
	v_add3_u32 v165, v165, v168, s92
	v_lshl_add_u64 v[168:169], v[166:167], 0, v[138:139]
	global_store_short_d16_hi v[168:169], v165, off
	v_mul_f32_e32 v165, v74, v164
	v_bfe_u32 v168, v165, 16, 1
	v_add3_u32 v165, v165, v168, s92
	v_lshl_add_u64 v[168:169], v[166:167], 0, v[140:141]
	global_store_short_d16_hi v[168:169], v165, off
	v_mul_f32_e32 v165, v75, v164
	v_bfe_u32 v168, v165, 16, 1
	v_add3_u32 v165, v165, v168, s92
	v_lshl_add_u64 v[168:169], v[166:167], 0, v[142:143]
	global_store_short_d16_hi v[168:169], v165, off
	v_mul_f32_e32 v165, v76, v164
	v_bfe_u32 v168, v165, 16, 1
	v_add3_u32 v165, v165, v168, s92
	v_lshl_add_u64 v[168:169], v[166:167], 0, v[144:145]
	global_store_short_d16_hi v[168:169], v165, off
	v_mul_f32_e32 v165, v77, v164
	v_bfe_u32 v168, v165, 16, 1
	v_add3_u32 v165, v165, v168, s92
	v_lshl_add_u64 v[168:169], v[166:167], 0, v[146:147]
	global_store_short_d16_hi v[168:169], v165, off
	v_mul_f32_e32 v165, v70, v164
	v_bfe_u32 v168, v165, 16, 1
	v_add3_u32 v165, v165, v168, s92
	v_lshl_add_u64 v[168:169], v[166:167], 0, v[148:149]
	global_store_short_d16_hi v[168:169], v165, off
	v_mul_f32_e32 v165, v71, v164
	v_bfe_u32 v168, v165, 16, 1
	v_add3_u32 v165, v165, v168, s92
	v_lshl_add_u64 v[168:169], v[166:167], 0, v[150:151]
	global_store_short_d16_hi v[168:169], v165, off
	v_mul_f32_e32 v165, v72, v164
	v_bfe_u32 v168, v165, 16, 1
	v_add3_u32 v165, v165, v168, s92
	v_lshl_add_u64 v[168:169], v[166:167], 0, v[152:153]
	global_store_short_d16_hi v[168:169], v165, off
	v_mul_f32_e32 v165, v73, v164
	v_bfe_u32 v168, v165, 16, 1
	v_add3_u32 v165, v165, v168, s92
	v_lshl_add_u64 v[168:169], v[166:167], 0, v[154:155]
	global_store_short_d16_hi v[168:169], v165, off
	v_mul_f32_e32 v165, v66, v164
	v_bfe_u32 v168, v165, 16, 1
	v_add3_u32 v165, v165, v168, s92
	v_lshl_add_u64 v[168:169], v[166:167], 0, v[156:157]
	global_store_short_d16_hi v[168:169], v165, off
	v_mul_f32_e32 v165, v67, v164
	v_bfe_u32 v168, v165, 16, 1
	v_add3_u32 v165, v165, v168, s92
	v_lshl_add_u64 v[168:169], v[166:167], 0, v[158:159]
	global_store_short_d16_hi v[168:169], v165, off
	v_mul_f32_e32 v165, v68, v164
	v_bfe_u32 v168, v165, 16, 1
	v_add3_u32 v165, v165, v168, s92
	v_lshl_add_u64 v[168:169], v[166:167], 0, v[160:161]
	v_mul_f32_e32 v164, v69, v164
	global_store_short_d16_hi v[168:169], v165, off
	v_bfe_u32 v165, v164, 16, 1
	v_add3_u32 v168, v164, v165, s92
	v_lshl_add_u64 v[164:165], v[166:167], 0, v[162:163]
	global_store_short_d16_hi v[164:165], v168, off
	v_mov_b32_e32 v164, 1.0
	s_and_b64 vcc, exec, s[44:45]
	v_mov_b32_e32 v165, 1.0
	s_cbranch_vccnz .LBB0_463
	v_mov_b32_e32 v165, v236
; DI unsigned f2bf(float f) { unsigned u = __builtin_bit_cast(unsigned, f); return (u + 0x7fffu + ((u >> 16) & 1u)) >> 16; }
;     DI void operator()(const f32x4 (&acc)[2][2][4][2], const Unit& u, int wr, int wc, int fr, int fq) const {
;     ...
;                     for (int m = 0; m < 4; ++m) { const int row = rowi + ai * HALF + m * 16;
;                         const float rs_ = ss_in ? rsqrtf(ss_in[row0 + ai * HALF + m * 16] * (1.f / DM) + EPS) : 1.f;
; #pragma unroll
;                         for (int bj = 0; bj < 2; ++bj)
; #pragma unroll
;                             for (int n = 0; n < 2; ++n)
; #pragma unroll
;                                 for (int j = 0; j < 4; ++j) base[(size_t)(col0 + bj * HALF + 4 * n + j) * ldt + row] = (bf16_t)f2bf(acc[ai][bj][m][n][j] * rs_); }
.LBB0_463:
	v_mul_f32_e32 v168, v62, v165
	v_bfe_u32 v169, v168, 16, 1
	v_add3_u32 v168, v168, v169, s92
	s_mov_b64 s[12:13], 0x100
	global_store_short_d16_hi v[134:135], v168, off offset:256
	v_mul_f32_e32 v168, v63, v165
	v_lshl_add_u64 v[166:167], v[132:133], 0, s[12:13]
	v_bfe_u32 v169, v168, 16, 1
	v_add3_u32 v170, v168, v169, s92
	v_lshl_add_u64 v[168:169], v[166:167], 0, v[0:1]
	global_store_short_d16_hi v[168:169], v170, off
	v_mul_f32_e32 v168, v64, v165
	v_bfe_u32 v169, v168, 16, 1
	v_add3_u32 v170, v168, v169, s92
	v_lshl_add_u64 v[168:169], v[166:167], 0, v[136:137]
	global_store_short_d16_hi v[168:169], v170, off
	v_mul_f32_e32 v168, v65, v165
	v_bfe_u32 v169, v168, 16, 1
	v_add3_u32 v170, v168, v169, s92
	v_lshl_add_u64 v[168:169], v[166:167], 0, v[138:139]
	global_store_short_d16_hi v[168:169], v170, off
	v_mul_f32_e32 v168, v58, v165
	v_bfe_u32 v169, v168, 16, 1
	v_add3_u32 v170, v168, v169, s92
	v_lshl_add_u64 v[168:169], v[166:167], 0, v[140:141]
	global_store_short_d16_hi v[168:169], v170, off
	v_mul_f32_e32 v168, v59, v165
	v_bfe_u32 v169, v168, 16, 1
	v_add3_u32 v170, v168, v169, s92
	v_lshl_add_u64 v[168:169], v[166:167], 0, v[142:143]
	global_store_short_d16_hi v[168:169], v170, off
	v_mul_f32_e32 v168, v60, v165
	v_bfe_u32 v169, v168, 16, 1
	v_add3_u32 v170, v168, v169, s92
	v_lshl_add_u64 v[168:169], v[166:167], 0, v[144:145]
	global_store_short_d16_hi v[168:169], v170, off
	v_mul_f32_e32 v168, v61, v165
	v_bfe_u32 v169, v168, 16, 1
	v_add3_u32 v170, v168, v169, s92
	v_lshl_add_u64 v[168:169], v[166:167], 0, v[146:147]
	global_store_short_d16_hi v[168:169], v170, off
	v_mul_f32_e32 v168, v54, v165
	v_bfe_u32 v169, v168, 16, 1
	v_add3_u32 v170, v168, v169, s92
	v_lshl_add_u64 v[168:169], v[166:167], 0, v[148:149]
	global_store_short_d16_hi v[168:169], v170, off
	v_mul_f32_e32 v168, v55, v165
	v_bfe_u32 v169, v168, 16, 1
	v_add3_u32 v170, v168, v169, s92
	v_lshl_add_u64 v[168:169], v[166:167], 0, v[150:151]
	global_store_short_d16_hi v[168:169], v170, off
	v_mul_f32_e32 v168, v56, v165
	v_bfe_u32 v169, v168, 16, 1
	v_add3_u32 v170, v168, v169, s92
	v_lshl_add_u64 v[168:169], v[166:167], 0, v[152:153]
	global_store_short_d16_hi v[168:169], v170, off
	v_mul_f32_e32 v168, v57, v165
	v_bfe_u32 v169, v168, 16, 1
	v_add3_u32 v170, v168, v169, s92
	v_lshl_add_u64 v[168:169], v[166:167], 0, v[154:155]
	global_store_short_d16_hi v[168:169], v170, off
	v_mul_f32_e32 v168, v50, v165
	v_bfe_u32 v169, v168, 16, 1
	v_add3_u32 v170, v168, v169, s92
	v_lshl_add_u64 v[168:169], v[166:167], 0, v[156:157]
	global_store_short_d16_hi v[168:169], v170, off
	v_mul_f32_e32 v168, v51, v165
	v_bfe_u32 v169, v168, 16, 1
	v_add3_u32 v170, v168, v169, s92
	v_lshl_add_u64 v[168:169], v[166:167], 0, v[158:159]
	global_store_short_d16_hi v[168:169], v170, off
	v_mul_f32_e32 v168, v52, v165
	v_bfe_u32 v169, v168, 16, 1
	v_add3_u32 v170, v168, v169, s92
	v_lshl_add_u64 v[168:169], v[166:167], 0, v[160:161]
	v_mul_f32_e32 v165, v53, v165
	global_store_short_d16_hi v[168:169], v170, off
	v_bfe_u32 v168, v165, 16, 1
	v_add3_u32 v165, v165, v168, s92
	v_lshl_add_u64 v[166:167], v[166:167], 0, v[162:163]
	s_and_b64 vcc, exec, s[44:45]
	global_store_short_d16_hi v[166:167], v165, off
	s_cbranch_vccnz .LBB0_465
	v_mov_b32_e32 v164, v237
; DI unsigned f2bf(float f) { unsigned u = __builtin_bit_cast(unsigned, f); return (u + 0x7fffu + ((u >> 16) & 1u)) >> 16; }
;     DI void operator()(const f32x4 (&acc)[2][2][4][2], const Unit& u, int wr, int wc, int fr, int fq) const {
;     ...
;                     for (int m = 0; m < 4; ++m) { const int row = rowi + ai * HALF + m * 16;
;                         const float rs_ = ss_in ? rsqrtf(ss_in[row0 + ai * HALF + m * 16] * (1.f / DM) + EPS) : 1.f;
; #pragma unroll
;                         for (int bj = 0; bj < 2; ++bj)
; #pragma unroll
;                             for (int n = 0; n < 2; ++n)
; #pragma unroll
;                                 for (int j = 0; j < 4; ++j) base[(size_t)(col0 + bj * HALF + 4 * n + j) * ldt + row] = (bf16_t)f2bf(acc[ai][bj][m][n][j] * rs_); }
.LBB0_465:
	v_mul_f32_e32 v165, v46, v164
	v_bfe_u32 v168, v165, 16, 1
	v_add3_u32 v165, v165, v168, s92
	s_mov_b64 s[12:13], 0x120
	global_store_short_d16_hi v[134:135], v165, off offset:288
	v_mul_f32_e32 v165, v47, v164
	v_lshl_add_u64 v[166:167], v[132:133], 0, s[12:13]
	v_bfe_u32 v168, v165, 16, 1
	v_add3_u32 v165, v165, v168, s92
	v_lshl_add_u64 v[168:169], v[166:167], 0, v[0:1]
	global_store_short_d16_hi v[168:169], v165, off
	v_mul_f32_e32 v165, v48, v164
	v_bfe_u32 v168, v165, 16, 1
	v_add3_u32 v165, v165, v168, s92
	v_lshl_add_u64 v[168:169], v[166:167], 0, v[136:137]
	global_store_short_d16_hi v[168:169], v165, off
	v_mul_f32_e32 v165, v49, v164
	v_bfe_u32 v168, v165, 16, 1
	v_add3_u32 v165, v165, v168, s92
	v_lshl_add_u64 v[168:169], v[166:167], 0, v[138:139]
	global_store_short_d16_hi v[168:169], v165, off
	v_mul_f32_e32 v165, v42, v164
	v_bfe_u32 v168, v165, 16, 1
	v_add3_u32 v165, v165, v168, s92
	v_lshl_add_u64 v[168:169], v[166:167], 0, v[140:141]
	global_store_short_d16_hi v[168:169], v165, off
	v_mul_f32_e32 v165, v43, v164
	v_bfe_u32 v168, v165, 16, 1
	v_add3_u32 v165, v165, v168, s92
	v_lshl_add_u64 v[168:169], v[166:167], 0, v[142:143]
	global_store_short_d16_hi v[168:169], v165, off
	v_mul_f32_e32 v165, v44, v164
	v_bfe_u32 v168, v165, 16, 1
	v_add3_u32 v165, v165, v168, s92
	v_lshl_add_u64 v[168:169], v[166:167], 0, v[144:145]
	global_store_short_d16_hi v[168:169], v165, off
	v_mul_f32_e32 v165, v45, v164
	v_bfe_u32 v168, v165, 16, 1
	v_add3_u32 v165, v165, v168, s92
	v_lshl_add_u64 v[168:169], v[166:167], 0, v[146:147]
	global_store_short_d16_hi v[168:169], v165, off
	v_mul_f32_e32 v165, v38, v164
	v_bfe_u32 v168, v165, 16, 1
	v_add3_u32 v165, v165, v168, s92
	v_lshl_add_u64 v[168:169], v[166:167], 0, v[148:149]
	global_store_short_d16_hi v[168:169], v165, off
	v_mul_f32_e32 v165, v39, v164
	v_bfe_u32 v168, v165, 16, 1
	v_add3_u32 v165, v165, v168, s92
	v_lshl_add_u64 v[168:169], v[166:167], 0, v[150:151]
	global_store_short_d16_hi v[168:169], v165, off
	v_mul_f32_e32 v165, v40, v164
	v_bfe_u32 v168, v165, 16, 1
	v_add3_u32 v165, v165, v168, s92
	v_lshl_add_u64 v[168:169], v[166:167], 0, v[152:153]
	global_store_short_d16_hi v[168:169], v165, off
	v_mul_f32_e32 v165, v41, v164
	v_bfe_u32 v168, v165, 16, 1
	v_add3_u32 v165, v165, v168, s92
	v_lshl_add_u64 v[168:169], v[166:167], 0, v[154:155]
	global_store_short_d16_hi v[168:169], v165, off
	v_mul_f32_e32 v165, v34, v164
	v_bfe_u32 v168, v165, 16, 1
	v_add3_u32 v165, v165, v168, s92
	v_lshl_add_u64 v[168:169], v[166:167], 0, v[156:157]
	global_store_short_d16_hi v[168:169], v165, off
	v_mul_f32_e32 v165, v35, v164
	v_bfe_u32 v168, v165, 16, 1
	v_add3_u32 v165, v165, v168, s92
	v_lshl_add_u64 v[168:169], v[166:167], 0, v[158:159]
	global_store_short_d16_hi v[168:169], v165, off
	v_mul_f32_e32 v165, v36, v164
	v_bfe_u32 v168, v165, 16, 1
	v_add3_u32 v165, v165, v168, s92
	v_lshl_add_u64 v[168:169], v[166:167], 0, v[160:161]
	v_mul_f32_e32 v164, v37, v164
	global_store_short_d16_hi v[168:169], v165, off
	v_bfe_u32 v165, v164, 16, 1
	v_add3_u32 v168, v164, v165, s92
	v_lshl_add_u64 v[164:165], v[166:167], 0, v[162:163]
	global_store_short_d16_hi v[164:165], v168, off
	v_mov_b32_e32 v164, 1.0
	s_and_b64 vcc, exec, s[44:45]
	v_mov_b32_e32 v165, 1.0
	s_cbranch_vccnz .LBB0_467
	v_mov_b32_e32 v165, v238
.LBB0_467:
	v_mul_f32_e32 v168, v30, v165
	v_bfe_u32 v169, v168, 16, 1
	v_add3_u32 v168, v168, v169, s92
	s_mov_b64 s[12:13], 0x140
	global_store_short_d16_hi v[134:135], v168, off offset:320
	v_mul_f32_e32 v168, v31, v165
	v_lshl_add_u64 v[166:167], v[132:133], 0, s[12:13]
	v_bfe_u32 v169, v168, 16, 1
	v_add3_u32 v170, v168, v169, s92
	v_lshl_add_u64 v[168:169], v[166:167], 0, v[0:1]
	global_store_short_d16_hi v[168:169], v170, off
	v_mul_f32_e32 v168, v32, v165
	v_bfe_u32 v169, v168, 16, 1
	v_add3_u32 v170, v168, v169, s92
	v_lshl_add_u64 v[168:169], v[166:167], 0, v[136:137]
	global_store_short_d16_hi v[168:169], v170, off
	v_mul_f32_e32 v168, v33, v165
	v_bfe_u32 v169, v168, 16, 1
	v_add3_u32 v170, v168, v169, s92
	v_lshl_add_u64 v[168:169], v[166:167], 0, v[138:139]
	global_store_short_d16_hi v[168:169], v170, off
	v_mul_f32_e32 v168, v26, v165
	v_bfe_u32 v169, v168, 16, 1
	v_add3_u32 v170, v168, v169, s92
	v_lshl_add_u64 v[168:169], v[166:167], 0, v[140:141]
	global_store_short_d16_hi v[168:169], v170, off
	v_mul_f32_e32 v168, v27, v165
	v_bfe_u32 v169, v168, 16, 1
	v_add3_u32 v170, v168, v169, s92
	v_lshl_add_u64 v[168:169], v[166:167], 0, v[142:143]
	global_store_short_d16_hi v[168:169], v170, off
	v_mul_f32_e32 v168, v28, v165
	v_bfe_u32 v169, v168, 16, 1
	v_add3_u32 v170, v168, v169, s92
	v_lshl_add_u64 v[168:169], v[166:167], 0, v[144:145]
	global_store_short_d16_hi v[168:169], v170, off
	v_mul_f32_e32 v168, v29, v165
	v_bfe_u32 v169, v168, 16, 1
	v_add3_u32 v170, v168, v169, s92
	v_lshl_add_u64 v[168:169], v[166:167], 0, v[146:147]
	global_store_short_d16_hi v[168:169], v170, off
	v_mul_f32_e32 v168, v22, v165
	v_bfe_u32 v169, v168, 16, 1
	v_add3_u32 v170, v168, v169, s92
	v_lshl_add_u64 v[168:169], v[166:167], 0, v[148:149]
	global_store_short_d16_hi v[168:169], v170, off
	v_mul_f32_e32 v168, v23, v165
	v_bfe_u32 v169, v168, 16, 1
	v_add3_u32 v170, v168, v169, s92
	v_lshl_add_u64 v[168:169], v[166:167], 0, v[150:151]
	global_store_short_d16_hi v[168:169], v170, off
	v_mul_f32_e32 v168, v24, v165
	v_bfe_u32 v169, v168, 16, 1
	v_add3_u32 v170, v168, v169, s92
	v_lshl_add_u64 v[168:169], v[166:167], 0, v[152:153]
	global_store_short_d16_hi v[168:169], v170, off
	v_mul_f32_e32 v168, v25, v165
	v_bfe_u32 v169, v168, 16, 1
	v_add3_u32 v170, v168, v169, s92
	v_lshl_add_u64 v[168:169], v[166:167], 0, v[154:155]
	global_store_short_d16_hi v[168:169], v170, off
	v_mul_f32_e32 v168, v18, v165
	v_bfe_u32 v169, v168, 16, 1
	v_add3_u32 v170, v168, v169, s92
	v_lshl_add_u64 v[168:169], v[166:167], 0, v[156:157]
	global_store_short_d16_hi v[168:169], v170, off
	v_mul_f32_e32 v168, v19, v165
	v_bfe_u32 v169, v168, 16, 1
	v_add3_u32 v170, v168, v169, s92
	v_lshl_add_u64 v[168:169], v[166:167], 0, v[158:159]
	global_store_short_d16_hi v[168:169], v170, off
	v_mul_f32_e32 v168, v20, v165
	v_bfe_u32 v169, v168, 16, 1
	v_add3_u32 v170, v168, v169, s92
	v_lshl_add_u64 v[168:169], v[166:167], 0, v[160:161]
	v_mul_f32_e32 v165, v21, v165
	global_store_short_d16_hi v[168:169], v170, off
	v_bfe_u32 v168, v165, 16, 1
	v_add3_u32 v165, v165, v168, s92
	v_lshl_add_u64 v[166:167], v[166:167], 0, v[162:163]
	s_and_b64 vcc, exec, s[44:45]
	global_store_short_d16_hi v[166:167], v165, off
	s_cbranch_vccnz .LBB0_469
	v_mov_b32_e32 v164, v239
